# G5 tiles: the epilogue's 8 row-sum loads issued from the tile-loop header ahead of the K loop, epilogue vmcnt(0) dropped, exit wait counted (16 stores)
# speedup vs baseline: 1.0031x; 1.0031x over previous
; template <class Epi, class Sched, bool ALIGN_EPI = false, bool SP2 = false>
; __device__ __forceinline__ void gemm_phase(PG8_LAS unsigned char* lds, const Gemm g, const Sched& S, const Epi& E) {
;     ...
;         const bool has_next = S.next(ui + 1, nxt);
;         const char* nA = has_next ? (const char*)g.A + (size_t)nxt.pm * tstep : cA; const char* nB = has_next ? (const char*)g.Bt + (size_t)nxt.pn * tstep : cB;
;     ...
;         for (int a = 0; a < 2; ++a)
; #pragma unroll
;             for (int b = 0; b < 2; ++b)
; #pragma unroll
;                 for (int m = 0; m < 4; ++m)
; #pragma unroll
;                     for (int n = 0; n < 2; ++n) acc[a][b][m][n] = (f32x4){0.f, 0.f, 0.f, 0.f};
;         cur = nxt; cA = nA; cB = nB; ++ui;
;     __device__ __forceinline__ void operator()(const f32x4 (&acc)[2][2][4][2], const Unit& u, int wr, int wc, int fr, int fq) const {
;     ...
;         float rsv[2][4];
; #pragma unroll
;         for (int ai = 0; ai < 2; ++ai)
; #pragma unroll
;             for (int m = 0; m < 4; ++m) rsv[ai][m] = ss[row0 + ai * 128 + m * 16];
.LBB0_866:
	s_ashr_i32 s15, s14, 31
	s_lshl_b64 s[16:17], s[14:15], 19
	s_add_u32 s16, s36, s16
	s_addc_u32 s17, s37, s17
	s_and_b64 s[18:19], s[8:9], exec
	s_cselect_b32 s15, s17, s25
	s_cselect_b32 s29, s16, s24
	s_ashr_i32 s13, s12, 31
	s_lshl_b64 s[18:19], s[12:13], 19
	s_add_u32 s18, s26, s18
	s_addc_u32 s19, s56, s19
	s_and_b64 s[22:23], s[8:9], exec
	s_cselect_b32 s13, s19, s1
	s_cselect_b32 s22, s18, s0
	s_add_u32 s24, s24, 0x40080
	s_addc_u32 s25, s25, 0
	s_add_u32 s23, s0, 0x100
	v_mov_b32_e32 v20, 0
	s_addc_u32 s35, s1, 0
	s_mov_b32 s60, -2
	v_mov_b32_e32 v21, v20
	v_mov_b32_e32 v22, v20
	v_mov_b32_e32 v23, v20
	v_mov_b32_e32 v24, v20
	v_mov_b32_e32 v25, v20
	v_mov_b32_e32 v26, v20
	v_mov_b32_e32 v27, v20
	v_mov_b32_e32 v36, v20
	v_mov_b32_e32 v37, v20
	v_mov_b32_e32 v38, v20
	v_mov_b32_e32 v39, v20
	v_mov_b32_e32 v40, v20
	v_mov_b32_e32 v41, v20
	v_mov_b32_e32 v42, v20
	v_mov_b32_e32 v43, v20
	v_mov_b32_e32 v52, v20
	v_mov_b32_e32 v53, v20
	v_mov_b32_e32 v54, v20
	v_mov_b32_e32 v55, v20
	v_mov_b32_e32 v56, v20
	v_mov_b32_e32 v57, v20
	v_mov_b32_e32 v58, v20
	v_mov_b32_e32 v59, v20
	v_lshl_add_u32 v12, s28, 8, v160
	v_mov_b32_e32 v13, 0
	v_lshl_add_u64 v[14:15], v[12:13], 2, s[4:5]
	global_load_dword v4, v[14:15], off
	global_load_dword v5, v[14:15], off offset:64
	global_load_dword v6, v[14:15], off offset:128
	global_load_dword v7, v[14:15], off offset:192
	global_load_dword v8, v[14:15], off offset:512
	global_load_dword v9, v[14:15], off offset:576
	global_load_dword v10, v[14:15], off offset:640
	global_load_dword v11, v[14:15], off offset:704
	v_mov_b32_e32 v68, v20
	v_mov_b32_e32 v69, v20
	v_mov_b32_e32 v70, v20
	v_mov_b32_e32 v71, v20
	v_mov_b32_e32 v72, v20
	v_mov_b32_e32 v73, v20
	v_mov_b32_e32 v74, v20
	v_mov_b32_e32 v75, v20
	v_mov_b32_e32 v28, v20
	v_mov_b32_e32 v29, v20
	v_mov_b32_e32 v30, v20
	v_mov_b32_e32 v31, v20
	v_mov_b32_e32 v32, v20
	v_mov_b32_e32 v33, v20
	v_mov_b32_e32 v34, v20
	v_mov_b32_e32 v35, v20
	v_mov_b32_e32 v44, v20
	v_mov_b32_e32 v45, v20
	v_mov_b32_e32 v46, v20
	v_mov_b32_e32 v47, v20
	v_mov_b32_e32 v48, v20
	v_mov_b32_e32 v49, v20
	v_mov_b32_e32 v50, v20
	v_mov_b32_e32 v51, v20
	v_mov_b32_e32 v60, v20
	v_mov_b32_e32 v61, v20
	v_mov_b32_e32 v62, v20
	v_mov_b32_e32 v63, v20
	v_mov_b32_e32 v64, v20
	v_mov_b32_e32 v65, v20
	v_mov_b32_e32 v66, v20
	v_mov_b32_e32 v67, v20
	v_mov_b32_e32 v76, v20
	v_mov_b32_e32 v77, v20
	v_mov_b32_e32 v78, v20
	v_mov_b32_e32 v79, v20
	v_mov_b32_e32 v80, v20
	v_mov_b32_e32 v81, v20
	v_mov_b32_e32 v82, v20
	v_mov_b32_e32 v83, v20
	v_mov_b32_e32 v84, v20
	v_mov_b32_e32 v85, v20
	v_mov_b32_e32 v86, v20
	v_mov_b32_e32 v87, v20
	v_mov_b32_e32 v88, v20
	v_mov_b32_e32 v89, v20
	v_mov_b32_e32 v90, v20
	v_mov_b32_e32 v91, v20
	v_mov_b32_e32 v100, v20
	v_mov_b32_e32 v101, v20
	v_mov_b32_e32 v102, v20
	v_mov_b32_e32 v103, v20
	v_mov_b32_e32 v104, v20
	v_mov_b32_e32 v105, v20
	v_mov_b32_e32 v106, v20
	v_mov_b32_e32 v107, v20
	v_mov_b32_e32 v116, v20
	v_mov_b32_e32 v117, v20
	v_mov_b32_e32 v118, v20
	v_mov_b32_e32 v119, v20
	v_mov_b32_e32 v120, v20
	v_mov_b32_e32 v121, v20
	v_mov_b32_e32 v122, v20
	v_mov_b32_e32 v123, v20
	v_mov_b32_e32 v132, v20
	v_mov_b32_e32 v133, v20
	v_mov_b32_e32 v134, v20
	v_mov_b32_e32 v135, v20
	v_mov_b32_e32 v136, v20
	v_mov_b32_e32 v137, v20
	v_mov_b32_e32 v138, v20
	v_mov_b32_e32 v139, v20
	v_mov_b32_e32 v92, v20
	v_mov_b32_e32 v93, v20
	v_mov_b32_e32 v94, v20
	v_mov_b32_e32 v95, v20
	v_mov_b32_e32 v96, v20
	v_mov_b32_e32 v97, v20
	v_mov_b32_e32 v98, v20
	v_mov_b32_e32 v99, v20
	v_mov_b32_e32 v108, v20
	v_mov_b32_e32 v109, v20
	v_mov_b32_e32 v110, v20
	v_mov_b32_e32 v111, v20
	v_mov_b32_e32 v112, v20
	v_mov_b32_e32 v113, v20
	v_mov_b32_e32 v114, v20
	v_mov_b32_e32 v115, v20
	v_mov_b32_e32 v124, v20
	v_mov_b32_e32 v125, v20
	v_mov_b32_e32 v126, v20
	v_mov_b32_e32 v127, v20
	v_mov_b32_e32 v128, v20
	v_mov_b32_e32 v129, v20
	v_mov_b32_e32 v130, v20
	v_mov_b32_e32 v131, v20
	v_mov_b32_e32 v140, v20
	v_mov_b32_e32 v141, v20
	v_mov_b32_e32 v142, v20
	v_mov_b32_e32 v143, v20
	v_mov_b32_e32 v144, v20
	v_mov_b32_e32 v145, v20
	v_mov_b32_e32 v146, v20
	v_mov_b32_e32 v147, v20

; __device__ __forceinline__ unsigned pk2(float lo, float hi) { return pg8::cvt_pk_bf16(lo, hi); }
;     __device__ __forceinline__ void operator()(const f32x4 (&acc)[2][2][4][2], const Unit& u, int wr, int wc, int fr, int fq) const {
;         const int row0 = u.pm * 256 + wr * 64 + fr, col0 = u.pn * 256 + wc * 32 + 8 * fq;
;         float rsv[2][4];
; #pragma unroll
;         for (int ai = 0; ai < 2; ++ai)
; #pragma unroll
;             for (int m = 0; m < 4; ++m) rsv[ai][m] = ss[row0 + ai * 128 + m * 16];
;         __builtin_amdgcn_sched_barrier(0);
; #pragma unroll
;         for (int ai = 0; ai < 2; ++ai)
; #pragma unroll
;             for (int m = 0; m < 4; ++m) { const int row = row0 + ai * 128 + m * 16; const float rs = rsqrtf(rsv[ai][m] * (1.f / DM) + EPS); bf16_t* rowp = H + (size_t)row * FF + col0;
; #pragma unroll
;                 for (int bj = 0; bj < 2; ++bj) { f32x4 v0 = acc[ai][bj][m][0] * rs, v1 = acc[ai][bj][m][1] * rs;
; #pragma unroll
;                     for (int k = 0; k < 4; ++k) { const float a = fmaxf(v0[k], 0.f), b = fmaxf(v1[k], 0.f); v0[k] = a * a; v1[k] = b * b; }
;                     u32x4 w; w.x = pk2(v0[0], v0[1]); w.y = pk2(v0[2], v0[3]); w.z = pk2(v1[0], v1[1]); w.w = pk2(v1[2], v1[3]);
;                     *(u32x4*)(rowp + bj * 128) = w; } }
;     }
.LBB0_870:
	v_lshl_add_u32 v156, s28, 8, v160
	v_or_b32_e32 v166, 16, v156
	v_ashrrev_i32_e32 v157, 31, v156
	v_ashrrev_i32_e32 v167, 31, v166
	v_or_b32_e32 v168, 32, v156
	v_lshl_add_u64 v[164:165], v[156:157], 2, s[4:5]
	v_lshl_add_u64 v[158:159], v[166:167], 2, s[4:5]
	v_ashrrev_i32_e32 v169, 31, v168
	v_mov_b32_e32 v172, v4
	v_mov_b32_e32 v173, v5
	v_lshl_add_u64 v[158:159], v[168:169], 2, s[4:5]
	v_mov_b32_e32 v174, v6
	v_or_b32_e32 v158, 48, v156
	v_ashrrev_i32_e32 v159, 31, v158
	v_lshl_add_u64 v[170:171], v[158:159], 2, s[4:5]
	v_mov_b32_e32 v175, v7
	v_mov_b32_e32 v176, v8
	v_mov_b32_e32 v177, v9
	v_mov_b32_e32 v178, v10
	s_nop 0
	v_mov_b32_e32 v164, v11
	v_lshl_or_b32 v170, s73, 8, v162
	s_nop 0
	v_fmamk_f32 v165, v172, 0x3a800000, v185
	v_mul_f32_e32 v171, 0x4b800000, v165
	v_cmp_gt_f32_e32 vcc, s86, v165
	v_lshlrev_b64 v[156:157], 13, v[156:157]
	v_lshl_add_u64 v[156:157], s[48:49], 0, v[156:157]
	v_cndmask_b32_e32 v165, v165, v171, vcc
	v_rsq_f32_e32 v165, v165
	v_ashrrev_i32_e32 v171, 31, v170
	v_lshlrev_b64 v[170:171], 1, v[170:171]
	v_lshl_add_u64 v[156:157], v[156:157], 0, v[170:171]
	v_mul_f32_e32 v172, 0x45800000, v165
	v_cndmask_b32_e32 v172, v165, v172, vcc
	v_pk_mul_f32 v[140:141], v[140:141], v[172:173] op_sel_hi:[1,0]
	v_pk_mul_f32 v[144:145], v[144:145], v[172:173] op_sel_hi:[1,0]
	v_pk_mul_f32 v[142:143], v[142:143], v[172:173] op_sel_hi:[1,0]
	v_max_f32_e32 v140, 0, v140
	v_pk_mul_f32 v[146:147], v[146:147], v[172:173] op_sel_hi:[1,0]
	v_mul_f32_e32 v165, v140, v140
	v_max_f32_e32 v140, 0, v145
	v_max_f32_e32 v141, 0, v141
	v_max_f32_e32 v142, 0, v142
	v_max_f32_e32 v144, 0, v144
	v_mul_f32_e32 v140, v140, v140
	v_mul_f32_e32 v145, v141, v141
	v_max_f32_e32 v141, 0, v146
	v_mul_f32_e32 v146, v142, v142
	v_max_f32_e32 v142, 0, v147
	v_max_f32_e32 v143, 0, v143
	v_pk_mul_f32 v[134:135], v[134:135], v[172:173] op_sel_hi:[1,0]
	v_pk_mul_f32 v[132:133], v[132:133], v[172:173] op_sel_hi:[1,0]
	v_mul_f32_e32 v144, v144, v144
	v_mul_f32_e32 v141, v141, v141
	v_mul_f32_e32 v142, v142, v142
	v_mul_f32_e32 v143, v143, v143
	v_cvt_pk_bf16_f32 v140, v144, v140
	v_pk_mul_f32 v[138:139], v[138:139], v[172:173] op_sel_hi:[1,0]
	v_pk_mul_f32 v[136:137], v[136:137], v[172:173] op_sel_hi:[1,0]
	v_max_f32_e32 v132, 0, v132
	v_max_f32_e32 v133, 0, v133
	v_max_f32_e32 v134, 0, v134
	v_cvt_pk_bf16_f32 v141, v141, v142
	v_cvt_pk_bf16_f32 v142, v165, v145
	v_cvt_pk_bf16_f32 v143, v146, v143
	global_store_dwordx4 v[156:157], v[140:143], off
	v_max_f32_e32 v136, 0, v136
	v_mul_f32_e32 v136, v136, v136
	v_mul_f32_e32 v140, v132, v132
	v_max_f32_e32 v132, 0, v137
	v_mul_f32_e32 v137, v133, v133
	v_max_f32_e32 v133, 0, v138
	v_mul_f32_e32 v138, v134, v134
	v_max_f32_e32 v134, 0, v139
	v_mul_f32_e32 v132, v132, v132
	v_mul_f32_e32 v133, v133, v133
	v_mul_f32_e32 v134, v134, v134
	v_cvt_pk_bf16_f32 v132, v136, v132
	v_cvt_pk_bf16_f32 v133, v133, v134
	v_fmamk_f32 v134, v173, 0x3a800000, v185
	v_mul_f32_e32 v136, 0x4b800000, v134
	v_cmp_gt_f32_e32 vcc, s86, v134
	v_max_f32_e32 v135, 0, v135
	v_mul_f32_e32 v135, v135, v135
	v_cndmask_b32_e32 v134, v134, v136, vcc
	v_rsq_f32_e32 v136, v134
	v_cvt_pk_bf16_f32 v134, v140, v137
	v_cvt_pk_bf16_f32 v135, v138, v135
	global_store_dwordx4 v[156:157], v[132:135], off offset:256
	s_mov_b64 s[0:1], 0x100000
	s_nop 0
	v_mul_f32_e32 v132, 0x45800000, v136
	v_cndmask_b32_e32 v132, v136, v132, vcc
	v_pk_mul_f32 v[124:125], v[124:125], v[132:133] op_sel_hi:[1,0]
	v_pk_mul_f32 v[128:129], v[128:129], v[132:133] op_sel_hi:[1,0]
	v_pk_mul_f32 v[126:127], v[126:127], v[132:133] op_sel_hi:[1,0]
	v_max_f32_e32 v124, 0, v124
	v_lshlrev_b64 v[134:135], 13, v[166:167]
	v_pk_mul_f32 v[130:131], v[130:131], v[132:133] op_sel_hi:[1,0]
	v_mul_f32_e32 v133, v124, v124
	v_max_f32_e32 v124, 0, v129
	v_max_f32_e32 v125, 0, v125
	v_max_f32_e32 v126, 0, v126
	v_lshl_add_u64 v[134:135], s[48:49], 0, v[134:135]
	v_max_f32_e32 v128, 0, v128
	v_mul_f32_e32 v124, v124, v124
	v_mul_f32_e32 v129, v125, v125
	v_max_f32_e32 v125, 0, v130
	v_mul_f32_e32 v130, v126, v126
	v_max_f32_e32 v126, 0, v131
	v_max_f32_e32 v127, 0, v127
	v_pk_mul_f32 v[118:119], v[118:119], v[132:133] op_sel_hi:[1,0]
	v_pk_mul_f32 v[116:117], v[116:117], v[132:133] op_sel_hi:[1,0]
	v_lshl_add_u64 v[134:135], v[134:135], 0, v[170:171]
	v_mul_f32_e32 v128, v128, v128
	v_mul_f32_e32 v125, v125, v125
	v_mul_f32_e32 v126, v126, v126
	v_mul_f32_e32 v127, v127, v127
	v_cvt_pk_bf16_f32 v124, v128, v124
	v_pk_mul_f32 v[122:123], v[122:123], v[132:133] op_sel_hi:[1,0]
	v_pk_mul_f32 v[120:121], v[120:121], v[132:133] op_sel_hi:[1,0]
	v_max_f32_e32 v116, 0, v116
	v_max_f32_e32 v117, 0, v117
	v_max_f32_e32 v118, 0, v118
	v_cvt_pk_bf16_f32 v125, v125, v126
	v_cvt_pk_bf16_f32 v126, v133, v129
	v_cvt_pk_bf16_f32 v127, v130, v127
	global_store_dwordx4 v[134:135], v[124:127], off
	v_max_f32_e32 v120, 0, v120
	v_mul_f32_e32 v120, v120, v120
	v_mul_f32_e32 v124, v116, v116
	v_max_f32_e32 v116, 0, v121
	v_mul_f32_e32 v121, v117, v117
	v_max_f32_e32 v117, 0, v122
	v_mul_f32_e32 v122, v118, v118
	v_max_f32_e32 v118, 0, v123
	v_mul_f32_e32 v116, v116, v116
	v_mul_f32_e32 v117, v117, v117
	v_mul_f32_e32 v118, v118, v118
	v_cvt_pk_bf16_f32 v116, v120, v116
	v_cvt_pk_bf16_f32 v117, v117, v118
	v_fmamk_f32 v118, v174, 0x3a800000, v185
	v_mul_f32_e32 v120, 0x4b800000, v118
	v_cmp_gt_f32_e32 vcc, s86, v118
	v_max_f32_e32 v119, 0, v119
	v_mul_f32_e32 v119, v119, v119
	v_cndmask_b32_e32 v118, v118, v120, vcc
	v_rsq_f32_e32 v120, v118
	v_cvt_pk_bf16_f32 v118, v124, v121
	v_cvt_pk_bf16_f32 v119, v122, v119
	global_store_dwordx4 v[134:135], v[116:119], off offset:256
	s_nop 1
	v_mul_f32_e32 v116, 0x45800000, v120
; __device__ __forceinline__ unsigned pk2(float lo, float hi) { return pg8::cvt_pk_bf16(lo, hi); }
;     __device__ __forceinline__ void operator()(const f32x4 (&acc)[2][2][4][2], const Unit& u, int wr, int wc, int fr, int fq) const {
;     ...
;         for (int ai = 0; ai < 2; ++ai)
; #pragma unroll
;             for (int m = 0; m < 4; ++m) { const int row = row0 + ai * 128 + m * 16; const float rs = rsqrtf(rsv[ai][m] * (1.f / DM) + EPS); bf16_t* rowp = H + (size_t)row * FF + col0;
; #pragma unroll
;                 for (int bj = 0; bj < 2; ++bj) { f32x4 v0 = acc[ai][bj][m][0] * rs, v1 = acc[ai][bj][m][1] * rs;
; #pragma unroll
;                     for (int k = 0; k < 4; ++k) { const float a = fmaxf(v0[k], 0.f), b = fmaxf(v1[k], 0.f); v0[k] = a * a; v1[k] = b * b; }
;                     u32x4 w; w.x = pk2(v0[0], v0[1]); w.y = pk2(v0[2], v0[3]); w.z = pk2(v1[0], v1[1]); w.w = pk2(v1[2], v1[3]);
;                     *(u32x4*)(rowp + bj * 128) = w; } }
;     }
	v_cndmask_b32_e32 v116, v120, v116, vcc
	v_pk_mul_f32 v[108:109], v[108:109], v[116:117] op_sel_hi:[1,0]
	v_pk_mul_f32 v[112:113], v[112:113], v[116:117] op_sel_hi:[1,0]
	v_pk_mul_f32 v[110:111], v[110:111], v[116:117] op_sel_hi:[1,0]
	v_max_f32_e32 v108, 0, v108
	v_lshlrev_b64 v[118:119], 13, v[168:169]
	v_pk_mul_f32 v[114:115], v[114:115], v[116:117] op_sel_hi:[1,0]
	v_mul_f32_e32 v117, v108, v108
	v_max_f32_e32 v108, 0, v113
	v_max_f32_e32 v109, 0, v109
	v_max_f32_e32 v110, 0, v110
	v_lshl_add_u64 v[118:119], s[48:49], 0, v[118:119]
	v_max_f32_e32 v112, 0, v112
	v_mul_f32_e32 v108, v108, v108
	v_mul_f32_e32 v113, v109, v109
	v_max_f32_e32 v109, 0, v114
	v_mul_f32_e32 v114, v110, v110
	v_max_f32_e32 v110, 0, v115
	v_max_f32_e32 v111, 0, v111
	v_pk_mul_f32 v[102:103], v[102:103], v[116:117] op_sel_hi:[1,0]
	v_pk_mul_f32 v[100:101], v[100:101], v[116:117] op_sel_hi:[1,0]
	v_lshl_add_u64 v[118:119], v[118:119], 0, v[170:171]
	v_mul_f32_e32 v112, v112, v112
	v_mul_f32_e32 v109, v109, v109
	v_mul_f32_e32 v110, v110, v110
	v_mul_f32_e32 v111, v111, v111
	v_cvt_pk_bf16_f32 v108, v112, v108
	v_pk_mul_f32 v[106:107], v[106:107], v[116:117] op_sel_hi:[1,0]
	v_pk_mul_f32 v[104:105], v[104:105], v[116:117] op_sel_hi:[1,0]
	v_max_f32_e32 v100, 0, v100
	v_max_f32_e32 v101, 0, v101
	v_max_f32_e32 v102, 0, v102
	v_cvt_pk_bf16_f32 v109, v109, v110
	v_cvt_pk_bf16_f32 v110, v117, v113
	v_cvt_pk_bf16_f32 v111, v114, v111
	global_store_dwordx4 v[118:119], v[108:111], off
	v_max_f32_e32 v104, 0, v104
	v_mul_f32_e32 v104, v104, v104
	v_mul_f32_e32 v108, v100, v100
	v_max_f32_e32 v100, 0, v105
	v_mul_f32_e32 v105, v101, v101
	v_max_f32_e32 v101, 0, v106
	v_mul_f32_e32 v106, v102, v102
	v_max_f32_e32 v102, 0, v107
	v_mul_f32_e32 v100, v100, v100
	v_mul_f32_e32 v101, v101, v101
	v_mul_f32_e32 v102, v102, v102
	v_cvt_pk_bf16_f32 v100, v104, v100
	v_cvt_pk_bf16_f32 v101, v101, v102
	v_fmamk_f32 v102, v175, 0x3a800000, v185
	v_mul_f32_e32 v104, 0x4b800000, v102
	v_cmp_gt_f32_e32 vcc, s86, v102
	v_max_f32_e32 v103, 0, v103
	v_mul_f32_e32 v103, v103, v103
	v_cndmask_b32_e32 v102, v102, v104, vcc
	v_rsq_f32_e32 v104, v102
	v_cvt_pk_bf16_f32 v102, v108, v105
	v_cvt_pk_bf16_f32 v103, v106, v103
	global_store_dwordx4 v[118:119], v[100:103], off offset:256
	s_nop 1
	v_mul_f32_e32 v100, 0x45800000, v104
	v_cndmask_b32_e32 v100, v104, v100, vcc
	v_pk_mul_f32 v[92:93], v[92:93], v[100:101] op_sel_hi:[1,0]
	v_pk_mul_f32 v[96:97], v[96:97], v[100:101] op_sel_hi:[1,0]
	v_pk_mul_f32 v[94:95], v[94:95], v[100:101] op_sel_hi:[1,0]
	v_max_f32_e32 v92, 0, v92
	v_lshlrev_b64 v[102:103], 13, v[158:159]
	v_pk_mul_f32 v[98:99], v[98:99], v[100:101] op_sel_hi:[1,0]
	v_mul_f32_e32 v101, v92, v92
	v_max_f32_e32 v92, 0, v97
	v_max_f32_e32 v93, 0, v93
	v_max_f32_e32 v94, 0, v94
	v_lshl_add_u64 v[102:103], s[48:49], 0, v[102:103]
	v_max_f32_e32 v96, 0, v96
	v_mul_f32_e32 v92, v92, v92
	v_mul_f32_e32 v97, v93, v93
	v_max_f32_e32 v93, 0, v98
	v_mul_f32_e32 v98, v94, v94
	v_max_f32_e32 v94, 0, v99
	v_max_f32_e32 v95, 0, v95
	v_pk_mul_f32 v[86:87], v[86:87], v[100:101] op_sel_hi:[1,0]
	v_pk_mul_f32 v[84:85], v[84:85], v[100:101] op_sel_hi:[1,0]
	v_lshl_add_u64 v[102:103], v[102:103], 0, v[170:171]
	v_mul_f32_e32 v96, v96, v96
	v_mul_f32_e32 v93, v93, v93
	v_mul_f32_e32 v94, v94, v94
	v_mul_f32_e32 v95, v95, v95
	v_cvt_pk_bf16_f32 v92, v96, v92
	v_pk_mul_f32 v[90:91], v[90:91], v[100:101] op_sel_hi:[1,0]
	v_pk_mul_f32 v[88:89], v[88:89], v[100:101] op_sel_hi:[1,0]
	v_max_f32_e32 v84, 0, v84
	v_max_f32_e32 v85, 0, v85
	v_max_f32_e32 v86, 0, v86
	v_cvt_pk_bf16_f32 v93, v93, v94
	v_cvt_pk_bf16_f32 v94, v101, v97
	v_cvt_pk_bf16_f32 v95, v98, v95
	global_store_dwordx4 v[102:103], v[92:95], off
	v_max_f32_e32 v88, 0, v88
	v_mul_f32_e32 v88, v88, v88
	v_mul_f32_e32 v92, v84, v84
	v_max_f32_e32 v84, 0, v89
	v_mul_f32_e32 v89, v85, v85
	v_max_f32_e32 v85, 0, v90
	v_mul_f32_e32 v90, v86, v86
	v_max_f32_e32 v86, 0, v91
	v_mul_f32_e32 v84, v84, v84
	v_mul_f32_e32 v85, v85, v85
	v_mul_f32_e32 v86, v86, v86
	v_cvt_pk_bf16_f32 v84, v88, v84
	v_cvt_pk_bf16_f32 v85, v85, v86
	v_fmamk_f32 v86, v176, 0x3a800000, v185
	v_mul_f32_e32 v88, 0x4b800000, v86
	v_cmp_gt_f32_e32 vcc, s86, v86
	v_max_f32_e32 v87, 0, v87
	v_mul_f32_e32 v87, v87, v87
	v_cndmask_b32_e32 v86, v86, v88, vcc
	v_rsq_f32_e32 v88, v86
	v_cvt_pk_bf16_f32 v86, v92, v89
	v_cvt_pk_bf16_f32 v87, v90, v87
	global_store_dwordx4 v[102:103], v[84:87], off offset:256
	s_nop 1
	v_mul_f32_e32 v84, 0x45800000, v88
	v_cndmask_b32_e32 v84, v88, v84, vcc
	v_pk_mul_f32 v[76:77], v[76:77], v[84:85] op_sel_hi:[1,0]
	v_pk_mul_f32 v[80:81], v[80:81], v[84:85] op_sel_hi:[1,0]
	v_pk_mul_f32 v[78:79], v[78:79], v[84:85] op_sel_hi:[1,0]
	v_max_f32_e32 v76, 0, v76
	v_pk_mul_f32 v[82:83], v[82:83], v[84:85] op_sel_hi:[1,0]
	v_max_f32_e32 v80, 0, v80
	v_mul_f32_e32 v85, v76, v76
	v_max_f32_e32 v76, 0, v81
	v_max_f32_e32 v77, 0, v77
	v_max_f32_e32 v78, 0, v78
	v_lshl_add_u64 v[86:87], v[156:157], 0, s[0:1]
	v_mul_f32_e32 v80, v80, v80
	v_mul_f32_e32 v76, v76, v76
	v_mul_f32_e32 v81, v77, v77
	v_max_f32_e32 v77, 0, v82
	v_mul_f32_e32 v82, v78, v78
	v_max_f32_e32 v78, 0, v83
	s_mov_b32 s0, 0x100000
	v_mul_f32_e32 v77, v77, v77
	v_max_f32_e32 v79, 0, v79
	v_mul_f32_e32 v78, v78, v78
	v_cvt_pk_bf16_f32 v76, v80, v76
	v_add_co_u32_e32 v80, vcc, s0, v156
	v_pk_mul_f32 v[70:71], v[70:71], v[84:85] op_sel_hi:[1,0]
	v_pk_mul_f32 v[68:69], v[68:69], v[84:85] op_sel_hi:[1,0]
	v_mul_f32_e32 v79, v79, v79
	v_cvt_pk_bf16_f32 v77, v77, v78
	v_cvt_pk_bf16_f32 v78, v85, v81
	v_addc_co_u32_e32 v81, vcc, 0, v157, vcc
	v_pk_mul_f32 v[74:75], v[74:75], v[84:85] op_sel_hi:[1,0]
; __device__ __forceinline__ unsigned pk2(float lo, float hi) { return pg8::cvt_pk_bf16(lo, hi); }
;     __device__ __forceinline__ void operator()(const f32x4 (&acc)[2][2][4][2], const Unit& u, int wr, int wc, int fr, int fq) const {
;     ...
;         for (int ai = 0; ai < 2; ++ai)
; #pragma unroll
;             for (int m = 0; m < 4; ++m) { const int row = row0 + ai * 128 + m * 16; const float rs = rsqrtf(rsv[ai][m] * (1.f / DM) + EPS); bf16_t* rowp = H + (size_t)row * FF + col0;
; #pragma unroll
;                 for (int bj = 0; bj < 2; ++bj) { f32x4 v0 = acc[ai][bj][m][0] * rs, v1 = acc[ai][bj][m][1] * rs;
; #pragma unroll
;                     for (int k = 0; k < 4; ++k) { const float a = fmaxf(v0[k], 0.f), b = fmaxf(v1[k], 0.f); v0[k] = a * a; v1[k] = b * b; }
;                     u32x4 w; w.x = pk2(v0[0], v0[1]); w.y = pk2(v0[2], v0[3]); w.z = pk2(v1[0], v1[1]); w.w = pk2(v1[2], v1[3]);
;                     *(u32x4*)(rowp + bj * 128) = w; } }
;     }
	v_pk_mul_f32 v[72:73], v[72:73], v[84:85] op_sel_hi:[1,0]
	v_max_f32_e32 v68, 0, v68
	v_max_f32_e32 v69, 0, v69
	v_max_f32_e32 v70, 0, v70
	v_cvt_pk_bf16_f32 v79, v82, v79
	global_store_dwordx4 v[80:81], v[76:79], off
	v_max_f32_e32 v72, 0, v72
	v_mul_f32_e32 v72, v72, v72
	v_mul_f32_e32 v76, v68, v68
	v_max_f32_e32 v68, 0, v73
	v_mul_f32_e32 v73, v69, v69
	v_max_f32_e32 v69, 0, v74
	v_mul_f32_e32 v74, v70, v70
	v_max_f32_e32 v70, 0, v75
	v_mul_f32_e32 v68, v68, v68
	v_mul_f32_e32 v69, v69, v69
	v_mul_f32_e32 v70, v70, v70
	v_cvt_pk_bf16_f32 v68, v72, v68
	v_cvt_pk_bf16_f32 v69, v69, v70
	v_fmamk_f32 v70, v177, 0x3a800000, v185
	v_mul_f32_e32 v72, 0x4b800000, v70
	v_cmp_gt_f32_e32 vcc, s86, v70
	v_max_f32_e32 v71, 0, v71
	v_mul_f32_e32 v71, v71, v71
	v_cndmask_b32_e32 v70, v70, v72, vcc
	v_rsq_f32_e32 v72, v70
	v_cvt_pk_bf16_f32 v70, v76, v73
	v_cvt_pk_bf16_f32 v71, v74, v71
	global_store_dwordx4 v[86:87], v[68:71], off offset:256
	s_mov_b64 s[0:1], 0x120000
	s_nop 0
	v_mul_f32_e32 v68, 0x45800000, v72
	v_cndmask_b32_e32 v68, v72, v68, vcc
	v_pk_mul_f32 v[60:61], v[60:61], v[68:69] op_sel_hi:[1,0]
	v_pk_mul_f32 v[64:65], v[64:65], v[68:69] op_sel_hi:[1,0]
	v_pk_mul_f32 v[62:63], v[62:63], v[68:69] op_sel_hi:[1,0]
	v_max_f32_e32 v60, 0, v60
	v_pk_mul_f32 v[66:67], v[66:67], v[68:69] op_sel_hi:[1,0]
	v_max_f32_e32 v64, 0, v64
	v_mul_f32_e32 v69, v60, v60
	v_max_f32_e32 v60, 0, v65
	v_max_f32_e32 v61, 0, v61
	v_max_f32_e32 v62, 0, v62
	v_lshl_add_u64 v[70:71], v[156:157], 0, s[0:1]
	v_mul_f32_e32 v64, v64, v64
	v_mul_f32_e32 v60, v60, v60
	v_mul_f32_e32 v65, v61, v61
	v_max_f32_e32 v61, 0, v66
	v_mul_f32_e32 v66, v62, v62
	v_max_f32_e32 v62, 0, v67
	s_mov_b32 s0, 0x120000
	v_mul_f32_e32 v61, v61, v61
	v_max_f32_e32 v63, 0, v63
	v_mul_f32_e32 v62, v62, v62
	v_cvt_pk_bf16_f32 v60, v64, v60
	v_add_co_u32_e32 v64, vcc, s0, v156
	v_pk_mul_f32 v[54:55], v[54:55], v[68:69] op_sel_hi:[1,0]
	v_pk_mul_f32 v[52:53], v[52:53], v[68:69] op_sel_hi:[1,0]
	v_mul_f32_e32 v63, v63, v63
	v_cvt_pk_bf16_f32 v61, v61, v62
	v_cvt_pk_bf16_f32 v62, v69, v65
	v_addc_co_u32_e32 v65, vcc, 0, v157, vcc
	v_pk_mul_f32 v[58:59], v[58:59], v[68:69] op_sel_hi:[1,0]
	v_pk_mul_f32 v[56:57], v[56:57], v[68:69] op_sel_hi:[1,0]
	v_max_f32_e32 v52, 0, v52
	v_max_f32_e32 v53, 0, v53
	v_max_f32_e32 v54, 0, v54
	v_cvt_pk_bf16_f32 v63, v66, v63
	global_store_dwordx4 v[64:65], v[60:63], off
	v_max_f32_e32 v56, 0, v56
	v_mul_f32_e32 v56, v56, v56
	v_mul_f32_e32 v60, v52, v52
	v_max_f32_e32 v52, 0, v57
	v_mul_f32_e32 v57, v53, v53
	v_max_f32_e32 v53, 0, v58
	v_mul_f32_e32 v58, v54, v54
	v_max_f32_e32 v54, 0, v59
	v_mul_f32_e32 v52, v52, v52
	v_mul_f32_e32 v53, v53, v53
	v_mul_f32_e32 v54, v54, v54
	v_cvt_pk_bf16_f32 v52, v56, v52
	v_cvt_pk_bf16_f32 v53, v53, v54
	v_fmamk_f32 v54, v178, 0x3a800000, v185
	v_mul_f32_e32 v56, 0x4b800000, v54
	v_cmp_gt_f32_e32 vcc, s86, v54
	v_max_f32_e32 v55, 0, v55
	v_mul_f32_e32 v55, v55, v55
	v_cndmask_b32_e32 v54, v54, v56, vcc
	v_rsq_f32_e32 v56, v54
	v_cvt_pk_bf16_f32 v54, v60, v57
	v_cvt_pk_bf16_f32 v55, v58, v55
	global_store_dwordx4 v[70:71], v[52:55], off offset:256
	s_mov_b64 s[0:1], 0x140000
	s_nop 0
	v_mul_f32_e32 v52, 0x45800000, v56
	v_cndmask_b32_e32 v52, v56, v52, vcc
	v_pk_mul_f32 v[44:45], v[44:45], v[52:53] op_sel_hi:[1,0]
	v_pk_mul_f32 v[48:49], v[48:49], v[52:53] op_sel_hi:[1,0]
	v_pk_mul_f32 v[46:47], v[46:47], v[52:53] op_sel_hi:[1,0]
	v_max_f32_e32 v44, 0, v44
	v_pk_mul_f32 v[50:51], v[50:51], v[52:53] op_sel_hi:[1,0]
	v_max_f32_e32 v48, 0, v48
	v_mul_f32_e32 v53, v44, v44
	v_max_f32_e32 v44, 0, v49
	v_max_f32_e32 v45, 0, v45
	v_max_f32_e32 v46, 0, v46
	v_lshl_add_u64 v[54:55], v[156:157], 0, s[0:1]
	v_mul_f32_e32 v48, v48, v48
	v_mul_f32_e32 v44, v44, v44
	v_mul_f32_e32 v49, v45, v45
	v_max_f32_e32 v45, 0, v50
	v_mul_f32_e32 v50, v46, v46
; #define PG8_WAIT_V(n) asm volatile("s_waitcnt vmcnt(" #n ")" ::: "memory")
; #define PG8_BAR __builtin_amdgcn_s_barrier()
; __device__ __forceinline__ unsigned pk2(float lo, float hi) { return pg8::cvt_pk_bf16(lo, hi); }
; template <class Epi, class Sched, bool ALIGN_EPI = false, bool SP2 = false>
; __device__ __forceinline__ void gemm_phase(PG8_LAS unsigned char* lds, const Gemm g, const Sched& S, const Epi& E) {
;     ...
;         if constexpr (ALIGN_EPI) { if (wr == 0) PG8_BAR; }
;         if constexpr (!Epi::AFTER_DRAIN) { E(acc, cur, wr, wc, fr, fq); S.done(cur); }
;         if (!has_next) break;
; #pragma unroll
;         for (int a = 0; a < 2; ++a)
; #pragma unroll
;             for (int b = 0; b < 2; ++b)
; #pragma unroll
;                 for (int m = 0; m < 4; ++m)
; #pragma unroll
;                     for (int n = 0; n < 2; ++n) acc[a][b][m][n] = (f32x4){0.f, 0.f, 0.f, 0.f};
;         cur = nxt; cA = nA; cB = nB; ++ui;
;         if constexpr (ALIGN_EPI) { if (wr == 1) PG8_BAR; }
;     }
;     PG8_WAIT_V(0);
;     if constexpr (!ALIGN_EPI) { if (wr == 0) PG8_BAR; }
;     PG8_BAR;
;     __device__ __forceinline__ void operator()(const f32x4 (&acc)[2][2][4][2], const Unit& u, int wr, int wc, int fr, int fq) const {
;     ...
;         for (int ai = 0; ai < 2; ++ai)
; #pragma unroll
;             for (int m = 0; m < 4; ++m) { const int row = row0 + ai * 128 + m * 16; const float rs = rsqrtf(rsv[ai][m] * (1.f / DM) + EPS); bf16_t* rowp = H + (size_t)row * FF + col0;
; #pragma unroll
;                 for (int bj = 0; bj < 2; ++bj) { f32x4 v0 = acc[ai][bj][m][0] * rs, v1 = acc[ai][bj][m][1] * rs;
; #pragma unroll
;                     for (int k = 0; k < 4; ++k) { const float a = fmaxf(v0[k], 0.f), b = fmaxf(v1[k], 0.f); v0[k] = a * a; v1[k] = b * b; }
;                     u32x4 w; w.x = pk2(v0[0], v0[1]); w.y = pk2(v0[2], v0[3]); w.z = pk2(v1[0], v1[1]); w.w = pk2(v1[2], v1[3]);
;                     *(u32x4*)(rowp + bj * 128) = w; } }
;     }
	v_max_f32_e32 v46, 0, v51
	s_mov_b32 s0, 0x140000
	v_mul_f32_e32 v45, v45, v45
	v_max_f32_e32 v47, 0, v47
	v_mul_f32_e32 v46, v46, v46
	v_cvt_pk_bf16_f32 v44, v48, v44
	v_add_co_u32_e32 v48, vcc, s0, v156
	v_pk_mul_f32 v[38:39], v[38:39], v[52:53] op_sel_hi:[1,0]
	v_pk_mul_f32 v[36:37], v[36:37], v[52:53] op_sel_hi:[1,0]
	v_mul_f32_e32 v47, v47, v47
	v_cvt_pk_bf16_f32 v45, v45, v46
	v_cvt_pk_bf16_f32 v46, v53, v49
	v_addc_co_u32_e32 v49, vcc, 0, v157, vcc
	v_pk_mul_f32 v[42:43], v[42:43], v[52:53] op_sel_hi:[1,0]
	v_pk_mul_f32 v[40:41], v[40:41], v[52:53] op_sel_hi:[1,0]
	v_max_f32_e32 v36, 0, v36
	v_max_f32_e32 v37, 0, v37
	v_max_f32_e32 v38, 0, v38
	v_cvt_pk_bf16_f32 v47, v50, v47
	global_store_dwordx4 v[48:49], v[44:47], off
	v_max_f32_e32 v40, 0, v40
	v_mul_f32_e32 v40, v40, v40
	v_mul_f32_e32 v44, v36, v36
	v_max_f32_e32 v36, 0, v41
	v_mul_f32_e32 v41, v37, v37
	v_max_f32_e32 v37, 0, v42
	v_mul_f32_e32 v42, v38, v38
	v_max_f32_e32 v38, 0, v43
	v_mul_f32_e32 v36, v36, v36
	v_mul_f32_e32 v37, v37, v37
	v_mul_f32_e32 v38, v38, v38
	v_cvt_pk_bf16_f32 v36, v40, v36
	v_cvt_pk_bf16_f32 v37, v37, v38
	v_fmamk_f32 v38, v164, 0x3a800000, v185
	v_mul_f32_e32 v40, 0x4b800000, v38
	v_cmp_gt_f32_e32 vcc, s86, v38
	v_max_f32_e32 v39, 0, v39
	v_mul_f32_e32 v39, v39, v39
	v_cndmask_b32_e32 v38, v38, v40, vcc
	v_rsq_f32_e32 v40, v38
	v_cvt_pk_bf16_f32 v38, v44, v41
	v_cvt_pk_bf16_f32 v39, v42, v39
	global_store_dwordx4 v[54:55], v[36:39], off offset:256
	s_mov_b64 s[0:1], 0x160000
	s_nop 0
	v_mul_f32_e32 v36, 0x45800000, v40
	v_cndmask_b32_e32 v36, v40, v36, vcc
	v_pk_mul_f32 v[28:29], v[28:29], v[36:37] op_sel_hi:[1,0]
	v_pk_mul_f32 v[32:33], v[32:33], v[36:37] op_sel_hi:[1,0]
	v_pk_mul_f32 v[30:31], v[30:31], v[36:37] op_sel_hi:[1,0]
	v_max_f32_e32 v28, 0, v28
	v_pk_mul_f32 v[34:35], v[34:35], v[36:37] op_sel_hi:[1,0]
	v_max_f32_e32 v32, 0, v32
	v_mul_f32_e32 v37, v28, v28
	v_max_f32_e32 v28, 0, v33
	v_max_f32_e32 v29, 0, v29
	v_max_f32_e32 v30, 0, v30
	v_lshl_add_u64 v[38:39], v[156:157], 0, s[0:1]
	v_mul_f32_e32 v32, v32, v32
	v_mul_f32_e32 v28, v28, v28
	v_mul_f32_e32 v33, v29, v29
	v_max_f32_e32 v29, 0, v34
	v_mul_f32_e32 v34, v30, v30
	v_max_f32_e32 v30, 0, v35
	s_mov_b32 s0, 0x160000
	v_mul_f32_e32 v29, v29, v29
	v_max_f32_e32 v31, 0, v31
	v_mul_f32_e32 v30, v30, v30
	v_cvt_pk_bf16_f32 v28, v32, v28
	v_add_co_u32_e32 v32, vcc, s0, v156
	v_pk_mul_f32 v[22:23], v[22:23], v[36:37] op_sel_hi:[1,0]
	v_pk_mul_f32 v[20:21], v[20:21], v[36:37] op_sel_hi:[1,0]
	v_mul_f32_e32 v31, v31, v31
	v_cvt_pk_bf16_f32 v29, v29, v30
	v_cvt_pk_bf16_f32 v30, v37, v33
	v_addc_co_u32_e32 v33, vcc, 0, v157, vcc
	v_pk_mul_f32 v[26:27], v[26:27], v[36:37] op_sel_hi:[1,0]
	v_pk_mul_f32 v[24:25], v[24:25], v[36:37] op_sel_hi:[1,0]
	v_max_f32_e32 v20, 0, v20
	v_max_f32_e32 v21, 0, v21
	v_max_f32_e32 v22, 0, v22
	v_cvt_pk_bf16_f32 v31, v34, v31
	global_store_dwordx4 v[32:33], v[28:31], off
	v_max_f32_e32 v23, 0, v23
	v_max_f32_e32 v24, 0, v24
	v_mul_f32_e32 v28, v20, v20
	v_max_f32_e32 v20, 0, v25
	v_mul_f32_e32 v25, v21, v21
	v_max_f32_e32 v21, 0, v26
	v_mul_f32_e32 v26, v22, v22
	v_max_f32_e32 v22, 0, v27
	v_mul_f32_e32 v20, v20, v20
	v_mul_f32_e32 v21, v21, v21
	v_mul_f32_e32 v22, v22, v22
	v_mul_f32_e32 v23, v23, v23
	s_andn2_b64 vcc, exec, s[8:9]
	s_mov_b64 s[0:1], -1
	v_mul_f32_e32 v24, v24, v24
	v_cvt_pk_bf16_f32 v20, v24, v20
	v_cvt_pk_bf16_f32 v21, v21, v22
	v_cvt_pk_bf16_f32 v22, v28, v25
	v_cvt_pk_bf16_f32 v23, v26, v23
	global_store_dwordx4 v[38:39], v[20:23], off offset:256
	s_cbranch_vccnz .LBB0_859
	s_andn2_b64 vcc, exec, s[6:7]
	s_cbranch_vccnz .LBB0_858
	s_barrier
	s_branch .LBB0_858
.LBB0_873:
	s_waitcnt vmcnt(16)
	v_readlane_b32 s28, v255, 30
	v_readlane_b32 s29, v255, 31
	s_mov_b32 s73, 0x10000
	s_mov_b32 s35, 0x18000
	s_mov_b32 s72, 0xc000
	s_barrier
